# phase 0: the adaLN waves take no transpose tile any more (they are the phase's critical path); the 2816 remaining tiles go to the other 1760 waves
# baseline (speedup 1.0000x reference)
; __device__ __forceinline__ void phase0(const Params& P, unsigned char* smem) {
;     ...
;     {
;         const int stride = gridDim.x * 2;
;         int it = blockIdx.x * 2 + hb;
;         TItem cur, nxt; int Nc = 0, Nn = 0; float vn[8];
;         if (blockIdx.x * 2 < total) { lookup(it, nxt, Nn); transpose_load(nxt, Nn, vn); }
;         for (int base = blockIdx.x * 2; base < total; base += stride) {
;             float v[8];
; #pragma unroll
;             for (int i = 0; i < 8; ++i) v[i] = vn[i];
;             cur = nxt; Nc = Nn;
;             if (base + stride < total) { lookup(it + stride, nxt, Nn); transpose_load(nxt, Nn, vn); }
;             transpose_store(cur, v, scr);
;             it += stride;
;         }
;     }
.Ltr_ic:
	s_cmp_lg_u32 s17, 0
	s_cbranch_scc1 .Ltr_done
	s_mov_b32 s1, s18
	s_mov_b32 s2, 0
	s_add_u32 s19, s1, 0x0
	s_cmpk_lt_u32 s19, 0x580
	s_cbranch_scc1 .Ltr1_m0
	s_cmpk_lt_u32 s19, 0xb00
	s_cbranch_scc1 .Ltr1_m1
	s_cmpk_lt_u32 s19, 0x1080
	s_cbranch_scc1 .Ltr1_m2
	s_cmpk_lt_u32 s19, 0x1600
	s_cbranch_scc1 .Ltr1_m3
	s_cmpk_lt_u32 s19, 0x1b80
	s_cbranch_scc1 .Ltr1_m4
	s_cmpk_lt_u32 s19, 0x2100
	s_cbranch_scc1 .Ltr1_m5
	s_cmpk_lt_u32 s19, 0x2910
	s_cbranch_scc1 .Ltr1_m6
	s_cmpk_lt_u32 s19, 0x2990
	s_cbranch_scc1 .Ltr1_m7
	s_cmpk_lt_u32 s19, 0x2a90
	s_cbranch_scc1 .Ltr1_m8
	s_cmpk_lt_u32 s19, 0x2b90
	s_cbranch_scc1 .Ltr1_m9
	s_sub_u32 s3, s19, 0x2b90
	v_readlane_b32 s6, v251, 43
	v_readlane_b32 s7, v251, 44
	s_mov_b32 s13, 0x2c00000
	s_mov_b32 s14, 0
	s_branch .Ltr1_c1024_1024

; __device__ __forceinline__ void phase0(const Params& P, unsigned char* smem) {
;     ...
;         for (int base = blockIdx.x * 2; base < total; base += stride) {
;             float v[8];
; #pragma unroll
;             for (int i = 0; i < 8; ++i) v[i] = vn[i];
;             cur = nxt; Nc = Nn;
;             if (base + stride < total) { lookup(it + stride, nxt, Nn); transpose_load(nxt, Nn, vn); }
;             transpose_store(cur, v, scr);
;             it += stride;
;         }
.Ltr_le1:
	s_add_u32 s2, s2, 1
	s_cmp_lt_u32 s2, 0
	s_cbranch_scc1 .Ltr2_common
	s_cmp_lg_u32 s17, 0
	s_cbranch_scc1 .Ltr_last0f
	s_cmp_eq_u32 s2, 0
	s_cbranch_scc0 .Ltr2_stride
	s_add_u32 s1, s18, 0x0
	s_branch .Ltr2_chk

; __device__ __forceinline__ void phase0(const Params& P, unsigned char* smem) {
;     ...
;         for (int base = blockIdx.x * 2; base < total; base += stride) {
;             float v[8];
; #pragma unroll
;             for (int i = 0; i < 8; ++i) v[i] = vn[i];
;             cur = nxt; Nc = Nn;
;             if (base + stride < total) { lookup(it + stride, nxt, Nn); transpose_load(nxt, Nn, vn); }
;             transpose_store(cur, v, scr);
;             it += stride;
;         }
.Ltr_pe1:
.Ltr_loop:
	s_add_u32 s2, s2, 1
	s_cmp_lt_u32 s2, 0
	s_cbranch_scc1 .Ltr4_common
	s_cmp_lg_u32 s17, 0
	s_cbranch_scc1 .Ltr_last1
	s_cmp_eq_u32 s2, 0
	s_cbranch_scc0 .Ltr4_stride
	s_add_u32 s1, s18, 0x0
	s_branch .Ltr4_chk

; __device__ __forceinline__ void phase0(const Params& P, unsigned char* smem) {
;     ...
;     const int gtid = blockIdx.x * NTHR + threadIdx.x, gsz = gridDim.x * NTHR;
;     for (int e = gtid; e < NT + 2 * NL; e += gsz) ((float*)(P.ws + OFF_SS))[e] = 0.f;
.Ltr_pe5:
.Ltr_done:
	v_readlane_b32 s0, v251, 1
	v_readlane_b32 s1, v251, 2
	s_nop 3
	s_load_dword s2, s[0:1], 0x10
	s_waitcnt lgkmcnt(0)
	s_lshr_b32 s0, s2, 16
	s_and_b32 s0, 0xffff, s0
	s_cmp_lg_u32 s0, 0
	s_cselect_b64 s[0:1], -1, 0
	s_cmp_lg_u64 s[0:1], 0
	s_addc_u32 s30, s90, 0
	s_branch .Ltr_pad
	s_nop 0
	s_nop 0
